# loop-edge edit: attention loop exit test as scalar step-counter compare + scc branch
# baseline (speedup 1.0000x reference)
.LBB0_844:
	s_or_b64 exec, exec, s[48:49]
	s_add_i32 s33, s33, 1
	v_mov_b32_e32 v172, v133
	s_cmp_gt_u32 s33, s61
	s_cbranch_scc1 .LBB0_855
